# grid barrier: L1 invalidate issued early; on the leader path right after the cross-XCD arrival atomic with vmcnt(1) so it never delays the arrival
# speedup vs baseline: 1.0058x; 1.0058x over previous
; __device__ __forceinline__ unsigned xb_add(unsigned* p, unsigned v) { return __hip_atomic_fetch_add(p, v, __ATOMIC_RELAXED, __HIP_MEMORY_SCOPE_AGENT); }
; __device__ __forceinline__ void xcd_barrier(const XcdBarrier& b) {
;     ...
;             __builtin_amdgcn_fence(__ATOMIC_RELEASE, "agent");
;             asm volatile("s_waitcnt vmcnt(0)" ::: "memory");
;             const unsigned og = xb_add(&bar[XB_TOP], 1u);
;             const unsigned tg = og / nx;
.LBB0_1165:
	s_or_b64 exec, exec, s[18:19]
	buffer_inv sc1
	s_waitcnt vmcnt(1)

; __device__ __forceinline__ unsigned xb_ld(unsigned* p)              { return __hip_atomic_load(p, __ATOMIC_RELAXED, __HIP_MEMORY_SCOPE_AGENT); }
; __device__ __forceinline__ unsigned xb_add(unsigned* p, unsigned v) { return __hip_atomic_fetch_add(p, v, __ATOMIC_RELAXED, __HIP_MEMORY_SCOPE_AGENT); }
; #define XB_SPIN(cond, bar) do { unsigned _sp = 0; while (cond) { __builtin_amdgcn_s_sleep(1); \
;     if ((++_sp & 255u) == 0u) { if (xb_ld(&(bar)[XB_TMO])) break; if (_sp > XB_SPIN_CAP) { atomicAdd(&(bar)[XB_TMO], 1u); break; } } } } while (0)
; __device__ __forceinline__ void xcd_barrier(const XcdBarrier& b) {
;     ...
;             const unsigned og = xb_add(&bar[XB_TOP], 1u);
;             const unsigned tg = og / nx;
;             if (og + 1u == (tg + 1u) * nx) xb_add(&bar[XB_TOPGEN], 1u);
;             else XB_SPIN(xb_ld(&bar[XB_TOPGEN]) == tg, bar);
	v_readfirstlane_b32 s2, v2
	v_cvt_f32_u32_e32 v2, v0
	v_sub_u32_e32 v3, 0, v0
	v_add_u32_e32 v1, s2, v1
	v_readlane_b32 s2, v254, 46
	v_rcp_iflag_f32_e32 v2, v2
	v_readlane_b32 s3, v254, 47
	s_mov_b64 s[38:39], -1
	v_mul_f32_e32 v2, 0x4f7ffffe, v2
	v_cvt_u32_f32_e32 v2, v2
	v_mul_lo_u32 v3, v3, v2
	v_mul_hi_u32 v3, v2, v3
	v_add_u32_e32 v2, v2, v3
	v_mul_hi_u32 v2, v1, v2
	v_mul_lo_u32 v3, v2, v0
	v_sub_u32_e32 v3, v1, v3
	v_cmp_ge_u32_e32 vcc, v3, v0
	v_add_u32_e32 v4, 1, v2
	v_add_u32_e32 v1, 1, v1
	v_cndmask_b32_e32 v2, v2, v4, vcc
	v_sub_u32_e32 v4, v3, v0
	v_cndmask_b32_e32 v3, v3, v4, vcc
	v_cmp_ge_u32_e32 vcc, v3, v0
	v_add_u32_e32 v3, 1, v2
	s_nop 0
	v_cndmask_b32_e32 v2, v2, v3, vcc
	v_mul_lo_u32 v3, v0, v2
	v_add_u32_e32 v0, v3, v0
	v_cmp_ne_u32_e32 vcc, v1, v0
	v_mov_b64_e32 v[0:1], s[2:3]
	s_and_saveexec_b64 s[18:19], vcc
	s_cbranch_execz .LBB0_1177
	v_readlane_b32 s2, v254, 46
	v_readlane_b32 s3, v254, 47
	s_nop 4
	global_load_dword v0, v181, s[2:3] sc1
	s_mov_b64 s[2:3], 0
	s_waitcnt vmcnt(0)
	v_cmp_eq_u32_e32 vcc, v0, v2
	s_and_saveexec_b64 s[38:39], vcc
	s_cbranch_execz .LBB0_1176
	s_mov_b32 s4, 1
	s_mov_b64 s[40:41], 0
	s_branch .LBB0_1169
